# grid barrier: non-leader workgroups poll the cross-XCD release generation directly instead of waiting for their XCD leader to relay it
# speedup vs baseline: 1.0047x; 1.0047x over previous
; __device__ __forceinline__ unsigned xb_ld(unsigned* p)              { return __hip_atomic_load(p, __ATOMIC_RELAXED, __HIP_MEMORY_SCOPE_AGENT); }
; __device__ __forceinline__ unsigned xb_add(unsigned* p, unsigned v) { return __hip_atomic_fetch_add(p, v, __ATOMIC_RELAXED, __HIP_MEMORY_SCOPE_AGENT); }
; #define XB_SPIN(cond, bar) do { unsigned _sp = 0; while (cond) { __builtin_amdgcn_s_sleep(1); \
;     if ((++_sp & 255u) == 0u) { if (xb_ld(&(bar)[XB_TMO])) break; if (_sp > XB_SPIN_CAP) { atomicAdd(&(bar)[XB_TMO], 1u); break; } } } } while (0)
; __device__ __forceinline__ void xcd_barrier(const XcdBarrier& b) {
;     ...
;         const unsigned old = xb_add(&bar[XB_XSUB(b.x)], 1u);
;         const unsigned gen = old / nloc;
;         if (old + 1u == (gen + 1u) * nloc) {
;             __builtin_amdgcn_fence(__ATOMIC_RELEASE, "agent");
;             asm volatile("s_waitcnt vmcnt(0)" ::: "memory");
;             const unsigned og = xb_add(&bar[XB_TOP], 1u);
;             const unsigned tg = og / nx;
;             if (og + 1u == (tg + 1u) * nx) xb_add(&bar[XB_TOPGEN], 1u);
;             else XB_SPIN(xb_ld(&bar[XB_TOPGEN]) == tg, bar);
;             __builtin_amdgcn_fence(__ATOMIC_ACQUIRE, "agent");
;             xb_add(&bar[XB_XGEN(b.x)], 1u);
;             asm volatile("s_waitcnt vmcnt(0)" ::: "memory");
;         } else {
;             XB_SPIN(xb_ld(&bar[XB_XGEN(b.x)]) == gen, bar);
;             __builtin_amdgcn_fence(__ATOMIC_ACQUIRE, "agent");
.LBB0_134:
	v_readlane_b32 s4, v254, 9
	s_lshl_b32 s4, s4, 8
	v_readlane_b32 s6, v254, 7
	v_readlane_b32 s7, v254, 8
	s_add_u32 s4, s6, s4
	s_addc_u32 s5, s7, 0
	v_mov_b32_e32 v2, 0x1000
	v_mov_b32_e32 v4, 1
	global_atomic_add v4, v2, v4, s[4:5] offset:1024 sc0
	v_cvt_f32_u32_e32 v2, v3
	v_sub_u32_e32 v5, 0, v3
	v_rcp_iflag_f32_e32 v2, v2
	s_nop 0
	v_mul_f32_e32 v2, 0x4f7ffffe, v2
	v_cvt_u32_f32_e32 v2, v2
	v_mul_lo_u32 v5, v5, v2
	v_mul_hi_u32 v5, v2, v5
	v_add_u32_e32 v2, v2, v5
	s_waitcnt vmcnt(0)
	v_mul_hi_u32 v2, v4, v2
	v_mul_lo_u32 v5, v2, v3
	v_sub_u32_e32 v5, v4, v5
	v_add_u32_e32 v6, 1, v2
	v_cmp_ge_u32_e32 vcc, v5, v3
	v_add_u32_e32 v4, 1, v4
	s_nop 0
	v_cndmask_b32_e32 v2, v2, v6, vcc
	v_sub_u32_e32 v6, v5, v3
	v_cndmask_b32_e32 v5, v5, v6, vcc
	v_add_u32_e32 v6, 1, v2
	v_cmp_ge_u32_e32 vcc, v5, v3
	s_nop 1
	v_cndmask_b32_e32 v2, v2, v6, vcc
	v_mul_lo_u32 v5, v3, v2
	v_add_u32_e32 v3, v5, v3
	v_cmp_ne_u32_e32 vcc, v4, v3
	s_and_saveexec_b64 s[6:7], vcc
	s_xor_b64 s[6:7], exec, s[6:7]
	s_cbranch_execz .LBB0_148
	s_waitcnt lgkmcnt(0)
	v_readlane_b32 s10, v254, 7
	v_readlane_b32 s11, v254, 8
	v_mov_b32_e32 v1, 0
	s_add_u32 s10, s10, 0x3500
	s_addc_u32 s11, s11, 0
	global_load_dword v1, v1, s[10:11] sc1
	s_waitcnt vmcnt(0)
	v_cmp_eq_u32_e32 vcc, v1, v2
	s_and_saveexec_b64 s[8:9], vcc
	s_cbranch_execz .LBB0_147
	s_mov_b32 s24, 1
	s_mov_b64 s[14:15], 0
	v_mov_b32_e32 v1, 0
	s_branch .LBB0_138

; __device__ __forceinline__ unsigned xb_ld(unsigned* p)              { return __hip_atomic_load(p, __ATOMIC_RELAXED, __HIP_MEMORY_SCOPE_AGENT); }
; __device__ __forceinline__ unsigned xb_add(unsigned* p, unsigned v) { return __hip_atomic_fetch_add(p, v, __ATOMIC_RELAXED, __HIP_MEMORY_SCOPE_AGENT); }
; #define XB_SPIN(cond, bar) do { unsigned _sp = 0; while (cond) { __builtin_amdgcn_s_sleep(1); \
;     if ((++_sp & 255u) == 0u) { if (xb_ld(&(bar)[XB_TMO])) break; if (_sp > XB_SPIN_CAP) { atomicAdd(&(bar)[XB_TMO], 1u); break; } } } } while (0)
; __device__ __forceinline__ void xcd_barrier(const XcdBarrier& b) {
;     ...
;         const unsigned old = xb_add(&bar[XB_XSUB(b.x)], 1u);
;         const unsigned gen = old / nloc;
;         if (old + 1u == (gen + 1u) * nloc) {
;             __builtin_amdgcn_fence(__ATOMIC_RELEASE, "agent");
;             asm volatile("s_waitcnt vmcnt(0)" ::: "memory");
;             const unsigned og = xb_add(&bar[XB_TOP], 1u);
;             const unsigned tg = og / nx;
;             if (og + 1u == (tg + 1u) * nx) xb_add(&bar[XB_TOPGEN], 1u);
;             else XB_SPIN(xb_ld(&bar[XB_TOPGEN]) == tg, bar);
;             __builtin_amdgcn_fence(__ATOMIC_ACQUIRE, "agent");
;             xb_add(&bar[XB_XGEN(b.x)], 1u);
;             asm volatile("s_waitcnt vmcnt(0)" ::: "memory");
;         } else {
;             XB_SPIN(xb_ld(&bar[XB_XGEN(b.x)]) == gen, bar);
;             __builtin_amdgcn_fence(__ATOMIC_ACQUIRE, "agent");
.LBB0_624:
	v_readlane_b32 s4, v254, 9
	s_lshl_b32 s4, s4, 8
	v_readlane_b32 s6, v254, 7
	v_readlane_b32 s7, v254, 8
	s_add_u32 s4, s6, s4
	s_addc_u32 s5, s7, 0
	v_mov_b32_e32 v2, 0x1000
	v_mov_b32_e32 v4, 1
	global_atomic_add v4, v2, v4, s[4:5] offset:1024 sc0
	v_cvt_f32_u32_e32 v2, v3
	v_sub_u32_e32 v5, 0, v3
	v_rcp_iflag_f32_e32 v2, v2
	s_nop 0
	v_mul_f32_e32 v2, 0x4f7ffffe, v2
	v_cvt_u32_f32_e32 v2, v2
	v_mul_lo_u32 v5, v5, v2
	v_mul_hi_u32 v5, v2, v5
	v_add_u32_e32 v2, v2, v5
	s_waitcnt vmcnt(0)
	v_mul_hi_u32 v2, v4, v2
	v_mul_lo_u32 v5, v2, v3
	v_sub_u32_e32 v5, v4, v5
	v_add_u32_e32 v6, 1, v2
	v_cmp_ge_u32_e32 vcc, v5, v3
	v_add_u32_e32 v4, 1, v4
	s_nop 0
	v_cndmask_b32_e32 v2, v2, v6, vcc
	v_sub_u32_e32 v6, v5, v3
	v_cndmask_b32_e32 v5, v5, v6, vcc
	v_add_u32_e32 v6, 1, v2
	v_cmp_ge_u32_e32 vcc, v5, v3
	s_nop 1
	v_cndmask_b32_e32 v2, v2, v6, vcc
	v_mul_lo_u32 v5, v3, v2
	v_add_u32_e32 v3, v5, v3
	v_cmp_ne_u32_e32 vcc, v4, v3
	s_and_saveexec_b64 s[6:7], vcc
	s_xor_b64 s[6:7], exec, s[6:7]
	s_cbranch_execz .LBB0_638
	s_waitcnt lgkmcnt(0)
	v_readlane_b32 s10, v254, 7
	v_readlane_b32 s11, v254, 8
	v_mov_b32_e32 v1, 0
	s_add_u32 s10, s10, 0x3500
	s_addc_u32 s11, s11, 0
	global_load_dword v1, v1, s[10:11] sc1
	s_waitcnt vmcnt(0)
	v_cmp_eq_u32_e32 vcc, v1, v2
	s_and_saveexec_b64 s[8:9], vcc
	s_cbranch_execz .LBB0_637
	s_mov_b32 s22, 1
	s_mov_b64 s[12:13], 0
	v_mov_b32_e32 v1, 0
	s_branch .LBB0_628

; __device__ __forceinline__ unsigned xb_ld(unsigned* p)              { return __hip_atomic_load(p, __ATOMIC_RELAXED, __HIP_MEMORY_SCOPE_AGENT); }
; __device__ __forceinline__ unsigned xb_add(unsigned* p, unsigned v) { return __hip_atomic_fetch_add(p, v, __ATOMIC_RELAXED, __HIP_MEMORY_SCOPE_AGENT); }
; #define XB_SPIN(cond, bar) do { unsigned _sp = 0; while (cond) { __builtin_amdgcn_s_sleep(1); \
;     if ((++_sp & 255u) == 0u) { if (xb_ld(&(bar)[XB_TMO])) break; if (_sp > XB_SPIN_CAP) { atomicAdd(&(bar)[XB_TMO], 1u); break; } } } } while (0)
; __device__ __forceinline__ void xcd_barrier(const XcdBarrier& b) {
;     ...
;         const unsigned old = xb_add(&bar[XB_XSUB(b.x)], 1u);
;         const unsigned gen = old / nloc;
;         if (old + 1u == (gen + 1u) * nloc) {
;             __builtin_amdgcn_fence(__ATOMIC_RELEASE, "agent");
;             asm volatile("s_waitcnt vmcnt(0)" ::: "memory");
;             const unsigned og = xb_add(&bar[XB_TOP], 1u);
;             const unsigned tg = og / nx;
;             if (og + 1u == (tg + 1u) * nx) xb_add(&bar[XB_TOPGEN], 1u);
;             else XB_SPIN(xb_ld(&bar[XB_TOPGEN]) == tg, bar);
;             __builtin_amdgcn_fence(__ATOMIC_ACQUIRE, "agent");
;             xb_add(&bar[XB_XGEN(b.x)], 1u);
;             asm volatile("s_waitcnt vmcnt(0)" ::: "memory");
;         } else {
;             XB_SPIN(xb_ld(&bar[XB_XGEN(b.x)]) == gen, bar);
;             __builtin_amdgcn_fence(__ATOMIC_ACQUIRE, "agent");
.LBB0_3529:
	v_readlane_b32 s4, v254, 9
	s_lshl_b32 s4, s4, 8
	v_readlane_b32 s6, v254, 7
	v_readlane_b32 s7, v254, 8
	s_add_u32 s4, s6, s4
	s_addc_u32 s5, s7, 0
	v_mov_b32_e32 v1, 0x1000
	v_mov_b32_e32 v3, 1
	global_atomic_add v3, v1, v3, s[4:5] offset:1024 sc0
	v_cvt_f32_u32_e32 v1, v2
	v_sub_u32_e32 v4, 0, v2
	v_rcp_iflag_f32_e32 v1, v1
	s_nop 0
	v_mul_f32_e32 v1, 0x4f7ffffe, v1
	v_cvt_u32_f32_e32 v1, v1
	v_mul_lo_u32 v4, v4, v1
	v_mul_hi_u32 v4, v1, v4
	v_add_u32_e32 v1, v1, v4
	s_waitcnt vmcnt(0)
	v_mul_hi_u32 v1, v3, v1
	v_mul_lo_u32 v4, v1, v2
	v_sub_u32_e32 v4, v3, v4
	v_add_u32_e32 v5, 1, v1
	v_cmp_ge_u32_e32 vcc, v4, v2
	v_add_u32_e32 v3, 1, v3
	s_nop 0
	v_cndmask_b32_e32 v1, v1, v5, vcc
	v_sub_u32_e32 v5, v4, v2
	v_cndmask_b32_e32 v4, v4, v5, vcc
	v_add_u32_e32 v5, 1, v1
	v_cmp_ge_u32_e32 vcc, v4, v2
	s_nop 1
	v_cndmask_b32_e32 v1, v1, v5, vcc
	v_mul_lo_u32 v4, v2, v1
	v_add_u32_e32 v2, v4, v2
	v_cmp_ne_u32_e32 vcc, v3, v2
	s_and_saveexec_b64 s[6:7], vcc
	s_xor_b64 s[6:7], exec, s[6:7]
	s_cbranch_execz .LBB0_3543
	s_waitcnt lgkmcnt(0)
	v_readlane_b32 s10, v254, 7
	v_readlane_b32 s11, v254, 8
	v_mov_b32_e32 v0, 0
	s_add_u32 s10, s10, 0x3500
	s_addc_u32 s11, s11, 0
	global_load_dword v0, v0, s[10:11] sc1
	s_waitcnt vmcnt(0)
	v_cmp_eq_u32_e32 vcc, v0, v1
	s_and_saveexec_b64 s[8:9], vcc
	s_cbranch_execz .LBB0_3542
	s_mov_b32 s22, 1
	s_mov_b64 s[12:13], 0
	v_mov_b32_e32 v0, 0
	s_branch .LBB0_3533
